# P4 K-loop: LDS-DMA as SGPR base + lane offset, LDS read bases set once per unit (no address VALU in the load segments)
# speedup vs baseline: 1.0089x; 1.0015x over previous
.LBB0_533:
	s_add_u32 s31, s2, 0x100
	s_addc_u32 s35, s3, 0
	s_mov_b32 s59, -2
	v_add_u32_e32 v250, 0x10000, v248
	v_add_u32_e32 v251, 0x14000, v248
	v_add_u32_e32 v252, 0x18000, v248
	v_add_u32_e32 v253, 0x1c000, v248
	s_branch .LBB0_535

.LBB0_535:
	ds_read_b128 v[150:153], v250
	ds_read_b128 v[154:157], v250 offset:1024
	ds_read_b128 v[158:161], v250 offset:2048
	ds_read_b128 v[162:165], v250 offset:3072
	s_mov_b64 s[8:9], s[44:45]
	ds_read_b128 v[134:137], v251
	ds_read_b128 v[138:141], v251 offset:1024
	ds_read_b128 v[142:145], v251 offset:2048
	ds_read_b128 v[146:149], v251 offset:3072
	s_add_u32 s44, s8, 0x100
	s_addc_u32 s45, s9, 0
	s_cmp_eq_u32 s59, 12
	s_cselect_b64 s[48:49], -1, 0
	s_and_b64 s[2:3], s[48:49], exec
	s_cselect_b32 s3, s39, s35
	s_cselect_b32 s2, s38, s31
	s_cselect_b32 s47, s37, s45
	s_cselect_b32 s46, s36, s44
	s_add_i32 m0, s55, 0xc000
	ds_read_b128 v[166:169], v249
	ds_read_b128 v[170:173], v249 offset:1024
	ds_read_b128 v[174:177], v249 offset:2048
	ds_read_b128 v[178:181], v249 offset:3072
	ds_read_b128 v[182:185], v249 offset:4096
	ds_read_b128 v[186:189], v249 offset:5120
	ds_read_b128 v[190:193], v249 offset:6144
	ds_read_b128 v[194:197], v249 offset:7168
	global_load_lds_dwordx4 v214, s[8:9]
	s_add_i32 m0, s55, 0xe000
	s_nop 0
	global_load_lds_dwordx4 v216, s[8:9]
	s_waitcnt vmcnt(8)
	s_waitcnt lgkmcnt(0)
	s_setprio 1
	s_barrier
	v_mfma_f32_16x16x32_bf16 v[130:133], v[150:153], v[166:169], v[130:133]
	v_mfma_f32_16x16x32_bf16 v[126:129], v[158:161], v[166:169], v[126:129]
	v_mfma_f32_16x16x32_bf16 v[122:125], v[150:153], v[174:177], v[122:125]
	v_mfma_f32_16x16x32_bf16 v[118:121], v[158:161], v[174:177], v[118:121]
	v_mfma_f32_16x16x32_bf16 v[114:117], v[150:153], v[182:185], v[114:117]
	v_mfma_f32_16x16x32_bf16 v[110:113], v[158:161], v[182:185], v[110:113]
	v_mfma_f32_16x16x32_bf16 v[106:109], v[150:153], v[190:193], v[106:109]
	v_mfma_f32_16x16x32_bf16 v[102:105], v[158:161], v[190:193], v[102:105]
	v_mfma_f32_16x16x32_bf16 v[130:133], v[154:157], v[170:173], v[130:133]
	v_mfma_f32_16x16x32_bf16 v[126:129], v[162:165], v[170:173], v[126:129]
	v_mfma_f32_16x16x32_bf16 v[122:125], v[154:157], v[178:181], v[122:125]
	v_mfma_f32_16x16x32_bf16 v[118:121], v[162:165], v[178:181], v[118:121]
	v_mfma_f32_16x16x32_bf16 v[114:117], v[154:157], v[186:189], v[114:117]
	v_mfma_f32_16x16x32_bf16 v[110:113], v[162:165], v[186:189], v[110:113]
	v_mfma_f32_16x16x32_bf16 v[106:109], v[154:157], v[194:197], v[106:109]
	v_mfma_f32_16x16x32_bf16 v[102:105], v[162:165], v[194:197], v[102:105]
	v_mfma_f32_16x16x32_bf16 v[98:101], v[134:137], v[166:169], v[98:101]
	v_mfma_f32_16x16x32_bf16 v[94:97], v[142:145], v[166:169], v[94:97]
	v_mfma_f32_16x16x32_bf16 v[90:93], v[134:137], v[174:177], v[90:93]
	v_mfma_f32_16x16x32_bf16 v[86:89], v[142:145], v[174:177], v[86:89]
	v_mfma_f32_16x16x32_bf16 v[82:85], v[134:137], v[182:185], v[82:85]
	v_mfma_f32_16x16x32_bf16 v[78:81], v[142:145], v[182:185], v[78:81]
	v_mfma_f32_16x16x32_bf16 v[74:77], v[134:137], v[190:193], v[74:77]
	v_mfma_f32_16x16x32_bf16 v[70:73], v[142:145], v[190:193], v[70:73]
	v_mfma_f32_16x16x32_bf16 v[98:101], v[138:141], v[170:173], v[98:101]
	v_mfma_f32_16x16x32_bf16 v[94:97], v[146:149], v[170:173], v[94:97]
	v_mfma_f32_16x16x32_bf16 v[90:93], v[138:141], v[178:181], v[90:93]
	v_mfma_f32_16x16x32_bf16 v[86:89], v[146:149], v[178:181], v[86:89]
	v_mfma_f32_16x16x32_bf16 v[82:85], v[138:141], v[186:189], v[82:85]
	v_mfma_f32_16x16x32_bf16 v[78:81], v[146:149], v[186:189], v[78:81]
	v_mfma_f32_16x16x32_bf16 v[74:77], v[138:141], v[194:197], v[74:77]
	v_mfma_f32_16x16x32_bf16 v[70:73], v[146:149], v[194:197], v[70:73]
	s_setprio 0
	s_barrier
	ds_read_b128 v[190:193], v249 offset:16384
	ds_read_b128 v[194:197], v249 offset:17408
	ds_read_b128 v[182:185], v249 offset:18432
	ds_read_b128 v[186:189], v249 offset:19456
	ds_read_b128 v[174:177], v249 offset:20480
	ds_read_b128 v[178:181], v249 offset:21504
	ds_read_b128 v[166:169], v249 offset:22528
	ds_read_b128 v[170:173], v249 offset:23552
	s_and_b64 s[8:9], s[6:7], s[48:49]
	s_mov_b64 s[48:49], -1
	s_and_b64 vcc, exec, s[8:9]
	s_cbranch_vccnz .LBB0_537
	s_add_u32 s68, s2, 0x80000
	s_addc_u32 s69, s3, 0
	s_add_i32 m0, s55, 0x10000
	s_nop 0
	global_load_lds_dwordx4 v204, s[2:3]
	s_add_i32 m0, s55, 0x12000
	s_nop 0
	global_load_lds_dwordx4 v210, s[2:3]
	s_add_i32 m0, s55, 0x14000
	s_nop 0
	global_load_lds_dwordx4 v204, s[68:69]
	s_add_i32 m0, s55, 0x16000
	s_mov_b64 s[48:49], 0
	global_load_lds_dwordx4 v210, s[68:69]
	s_mov_b32 m0, s55
	s_nop 0
	global_load_lds_dwordx4 v202, s[46:47]
	s_add_i32 m0, s55, 0x2000
	s_nop 0
	global_load_lds_dwordx4 v208, s[46:47]
	s_waitcnt vmcnt(8)

.LBB0_539:
	s_waitcnt lgkmcnt(0)
	s_xor_b64 s[48:49], s[8:9], -1
	s_setprio 1
	s_barrier
	v_mfma_f32_16x16x32_bf16 v[66:69], v[150:153], v[190:193], v[66:69]
	v_mfma_f32_16x16x32_bf16 v[62:65], v[158:161], v[190:193], v[62:65]
	v_mfma_f32_16x16x32_bf16 v[58:61], v[150:153], v[182:185], v[58:61]
	v_mfma_f32_16x16x32_bf16 v[54:57], v[158:161], v[182:185], v[54:57]
	v_mfma_f32_16x16x32_bf16 v[50:53], v[150:153], v[174:177], v[50:53]
	v_mfma_f32_16x16x32_bf16 v[46:49], v[158:161], v[174:177], v[46:49]
	v_mfma_f32_16x16x32_bf16 v[42:45], v[150:153], v[166:169], v[42:45]
	v_mfma_f32_16x16x32_bf16 v[38:41], v[158:161], v[166:169], v[38:41]
	v_mfma_f32_16x16x32_bf16 v[66:69], v[154:157], v[194:197], v[66:69]
	v_mfma_f32_16x16x32_bf16 v[62:65], v[162:165], v[194:197], v[62:65]
	v_mfma_f32_16x16x32_bf16 v[58:61], v[154:157], v[186:189], v[58:61]
	v_mfma_f32_16x16x32_bf16 v[54:57], v[162:165], v[186:189], v[54:57]
	v_mfma_f32_16x16x32_bf16 v[50:53], v[154:157], v[178:181], v[50:53]
	v_mfma_f32_16x16x32_bf16 v[46:49], v[162:165], v[178:181], v[46:49]
	v_mfma_f32_16x16x32_bf16 v[42:45], v[154:157], v[170:173], v[42:45]
	v_mfma_f32_16x16x32_bf16 v[38:41], v[162:165], v[170:173], v[38:41]
	v_mfma_f32_16x16x32_bf16 v[34:37], v[134:137], v[190:193], v[34:37]
	v_mfma_f32_16x16x32_bf16 v[30:33], v[142:145], v[190:193], v[30:33]
	v_mfma_f32_16x16x32_bf16 v[26:29], v[134:137], v[182:185], v[26:29]
	v_mfma_f32_16x16x32_bf16 v[22:25], v[142:145], v[182:185], v[22:25]
	v_mfma_f32_16x16x32_bf16 v[18:21], v[134:137], v[174:177], v[18:21]
	v_mfma_f32_16x16x32_bf16 v[14:17], v[142:145], v[174:177], v[14:17]
	v_mfma_f32_16x16x32_bf16 v[10:13], v[134:137], v[166:169], v[10:13]
	v_mfma_f32_16x16x32_bf16 v[4:7], v[142:145], v[166:169], v[6:9]
	v_mfma_f32_16x16x32_bf16 v[34:37], v[138:141], v[194:197], v[34:37]
	v_mfma_f32_16x16x32_bf16 v[30:33], v[146:149], v[194:197], v[30:33]
	v_mfma_f32_16x16x32_bf16 v[26:29], v[138:141], v[186:189], v[26:29]
	v_mfma_f32_16x16x32_bf16 v[22:25], v[146:149], v[186:189], v[22:25]
	v_mfma_f32_16x16x32_bf16 v[18:21], v[138:141], v[178:181], v[18:21]
	v_mfma_f32_16x16x32_bf16 v[14:17], v[146:149], v[178:181], v[14:17]
	v_mfma_f32_16x16x32_bf16 v[10:13], v[138:141], v[170:173], v[10:13]
	v_mfma_f32_16x16x32_bf16 v[4:7], v[146:149], v[170:173], v[4:7]
	s_setprio 0
	s_barrier
	ds_read_b128 v[150:153], v252
	ds_read_b128 v[154:157], v252 offset:1024
	ds_read_b128 v[158:161], v252 offset:2048
	ds_read_b128 v[162:165], v252 offset:3072
	ds_read_b128 v[134:137], v253
	ds_read_b128 v[138:141], v253 offset:1024
	ds_read_b128 v[142:145], v253 offset:2048
	ds_read_b128 v[146:149], v253 offset:3072
	ds_read_b128 v[190:193], v249 offset:32768
	ds_read_b128 v[194:197], v249 offset:33792
	ds_read_b128 v[182:185], v249 offset:34816
	ds_read_b128 v[186:189], v249 offset:35840
	ds_read_b128 v[174:177], v249 offset:36864
	ds_read_b128 v[178:181], v249 offset:37888
	ds_read_b128 v[166:169], v249 offset:38912
	ds_read_b128 v[170:173], v249 offset:39936
	v_cndmask_b32_e64 v3, 0, 1, s[48:49]
	v_cmp_ne_u32_e64 s[8:9], 1, v3
	s_andn2_b64 vcc, exec, s[48:49]
	s_mov_b64 s[48:49], -1
	s_cbranch_vccnz .LBB0_541
	s_add_u32 s46, s46, 0x80000
	s_addc_u32 s47, s47, 0
	s_add_i32 m0, s55, 0x4000
	s_mov_b64 s[48:49], 0
	global_load_lds_dwordx4 v202, s[46:47]
	s_add_i32 m0, s55, 0x6000
	s_nop 0
	global_load_lds_dwordx4 v208, s[46:47]
	s_waitcnt vmcnt(8)

.LBB0_543:
	s_waitcnt lgkmcnt(0)
	s_setprio 1
	s_barrier
	v_mfma_f32_16x16x32_bf16 v[130:133], v[150:153], v[190:193], v[130:133]
	v_mfma_f32_16x16x32_bf16 v[126:129], v[158:161], v[190:193], v[126:129]
	v_mfma_f32_16x16x32_bf16 v[122:125], v[150:153], v[182:185], v[122:125]
	v_mfma_f32_16x16x32_bf16 v[118:121], v[158:161], v[182:185], v[118:121]
	v_mfma_f32_16x16x32_bf16 v[114:117], v[150:153], v[174:177], v[114:117]
	v_mfma_f32_16x16x32_bf16 v[110:113], v[158:161], v[174:177], v[110:113]
	v_mfma_f32_16x16x32_bf16 v[106:109], v[150:153], v[166:169], v[106:109]
	v_mfma_f32_16x16x32_bf16 v[102:105], v[158:161], v[166:169], v[102:105]
	v_mfma_f32_16x16x32_bf16 v[130:133], v[154:157], v[194:197], v[130:133]
	v_mfma_f32_16x16x32_bf16 v[126:129], v[162:165], v[194:197], v[126:129]
	v_mfma_f32_16x16x32_bf16 v[122:125], v[154:157], v[186:189], v[122:125]
	v_mfma_f32_16x16x32_bf16 v[118:121], v[162:165], v[186:189], v[118:121]
	v_mfma_f32_16x16x32_bf16 v[114:117], v[154:157], v[178:181], v[114:117]
	v_mfma_f32_16x16x32_bf16 v[110:113], v[162:165], v[178:181], v[110:113]
	v_mfma_f32_16x16x32_bf16 v[106:109], v[154:157], v[170:173], v[106:109]
	v_mfma_f32_16x16x32_bf16 v[102:105], v[162:165], v[170:173], v[102:105]
	v_mfma_f32_16x16x32_bf16 v[98:101], v[134:137], v[190:193], v[98:101]
	v_mfma_f32_16x16x32_bf16 v[94:97], v[142:145], v[190:193], v[94:97]
	v_mfma_f32_16x16x32_bf16 v[90:93], v[134:137], v[182:185], v[90:93]
	v_mfma_f32_16x16x32_bf16 v[86:89], v[142:145], v[182:185], v[86:89]
	v_mfma_f32_16x16x32_bf16 v[82:85], v[134:137], v[174:177], v[82:85]
	v_mfma_f32_16x16x32_bf16 v[78:81], v[142:145], v[174:177], v[78:81]
	v_mfma_f32_16x16x32_bf16 v[74:77], v[134:137], v[166:169], v[74:77]
	v_mfma_f32_16x16x32_bf16 v[70:73], v[142:145], v[166:169], v[70:73]
	v_mfma_f32_16x16x32_bf16 v[98:101], v[138:141], v[194:197], v[98:101]
	v_mfma_f32_16x16x32_bf16 v[94:97], v[146:149], v[194:197], v[94:97]
	v_mfma_f32_16x16x32_bf16 v[90:93], v[138:141], v[186:189], v[90:93]
	v_mfma_f32_16x16x32_bf16 v[86:89], v[146:149], v[186:189], v[86:89]
	v_mfma_f32_16x16x32_bf16 v[82:85], v[138:141], v[178:181], v[82:85]
	v_mfma_f32_16x16x32_bf16 v[78:81], v[146:149], v[178:181], v[78:81]
	v_mfma_f32_16x16x32_bf16 v[74:77], v[138:141], v[170:173], v[74:77]
	v_mfma_f32_16x16x32_bf16 v[70:73], v[146:149], v[170:173], v[70:73]
	s_setprio 0
	s_barrier
	ds_read_b128 v[190:193], v249 offset:49152
	ds_read_b128 v[194:197], v249 offset:50176
	ds_read_b128 v[182:185], v249 offset:51200
	ds_read_b128 v[186:189], v249 offset:52224
	ds_read_b128 v[174:177], v249 offset:53248
	ds_read_b128 v[178:181], v249 offset:54272
	ds_read_b128 v[166:169], v249 offset:55296
	ds_read_b128 v[170:173], v249 offset:56320
	s_and_b64 vcc, exec, s[8:9]
	s_mov_b64 s[8:9], -1
	s_cbranch_vccnz .LBB0_545
	s_add_u32 s70, s2, 0x80
	s_addc_u32 s71, s3, 0
	s_add_u32 s2, s2, 0x80080
	s_addc_u32 s3, s3, 0
	s_sub_u32 s72, s46, 0x7ff80
	s_subb_u32 s73, s47, 0
	s_mov_b64 s[8:9], 0
	s_add_i32 m0, s55, 0x18000
	s_nop 0
	global_load_lds_dwordx4 v204, s[70:71]
	s_add_i32 m0, s55, 0x1a000
	s_nop 0
	global_load_lds_dwordx4 v210, s[70:71]
	s_add_i32 m0, s55, 0x1c000
	s_nop 0
	global_load_lds_dwordx4 v204, s[2:3]
	s_add_i32 m0, s55, 0x1e000
	s_nop 0
	global_load_lds_dwordx4 v210, s[2:3]
	s_add_i32 m0, s55, 0x8000
	s_nop 0
	global_load_lds_dwordx4 v202, s[72:73]
	s_add_i32 m0, s55, 0xa000
	s_nop 0
	global_load_lds_dwordx4 v208, s[72:73]
	s_waitcnt vmcnt(8)
